# attention epilogue: five sub-norm gain loads kept in flight with counted waits
# speedup vs baseline: 1.0206x; 1.0072x over previous
; DI float shflx(float v, int mask) { return __uint_as_float((unsigned)__builtin_amdgcn_ds_bpermute((lane_id_opaque() ^ mask) << 2, (int)__float_as_uint(v))); }
; template <bool DIFF> DI void attn_unit(LAS unsigned char* L, const bf16* Qh, int qpitch, const bf16* Kh, const bf16* Vh, int kvpitch, bf16* Oh, int opitch, ...
;     ...
;         if (mp == 0) {
;             float ss = 0.f;
; #pragma unroll
;             for (int d0 = 0; d0 < 4; ++d0)
; #pragma unroll
;                 for (int i = 0; i < 16; ++i) { const float o = y[d0][i] * inv - lam * exch[((qs * 4 + d0) * 16 + i) * 64 + le_]; y[d0][i] = o; ss += o * o; }
;             ss += shflx(ss, 32);
;             const float rr = rsqrtf(ss * (1.f / 128.f) + EPS) * postscale;
.LBB0_220:
	s_andn2_b64 vcc, exec, s[20:21]
	s_waitcnt lgkmcnt(0)
	s_barrier
	s_cbranch_vccnz .LBB0_166
	ds_read2st64_b32 v[78:79], v64 offset1:1
	ds_read2st64_b32 v[80:81], v64 offset0:2 offset1:3
	ds_read2st64_b32 v[82:83], v64 offset0:4 offset1:5
	ds_read2st64_b32 v[84:85], v64 offset0:6 offset1:7
	ds_read2st64_b32 v[90:91], v64 offset0:8 offset1:9
	ds_read2st64_b32 v[92:93], v64 offset0:10 offset1:11
	ds_read2st64_b32 v[96:97], v64 offset0:12 offset1:13
	ds_read2st64_b32 v[98:99], v64 offset0:14 offset1:15
	ds_read2st64_b32 v[100:101], v64 offset0:16 offset1:17
	ds_read2st64_b32 v[102:103], v64 offset0:18 offset1:19
	ds_read2st64_b32 v[104:105], v64 offset0:20 offset1:21
	ds_read2st64_b32 v[106:107], v64 offset0:22 offset1:23
	ds_read2st64_b32 v[108:109], v64 offset0:24 offset1:25
	ds_read2st64_b32 v[110:111], v64 offset0:26 offset1:27
	ds_read2st64_b32 v[112:113], v64 offset0:28 offset1:29
	ds_read2st64_b32 v[114:115], v64 offset0:30 offset1:31
	ds_read2st64_b32 v[116:117], v64 offset0:32 offset1:33
	ds_read2st64_b32 v[118:119], v64 offset0:34 offset1:35
	ds_read2st64_b32 v[120:121], v64 offset0:36 offset1:37
	ds_read2st64_b32 v[122:123], v64 offset0:38 offset1:39
	ds_read2st64_b32 v[124:125], v64 offset0:40 offset1:41
	ds_read2st64_b32 v[126:127], v64 offset0:42 offset1:43
	s_waitcnt vmcnt(3)
	ds_read2st64_b32 v[128:129], v64 offset0:44 offset1:45
	ds_read2st64_b32 v[130:131], v64 offset0:46 offset1:47
	s_waitcnt vmcnt(2)
	ds_read2st64_b32 v[132:133], v64 offset0:56 offset1:57
	ds_read2st64_b32 v[134:135], v64 offset0:58 offset1:59
	ds_read2st64_b32 v[66:67], v64 offset0:60 offset1:61
	ds_read2st64_b32 v[68:69], v64 offset0:62 offset1:63
	s_waitcnt vmcnt(1)
	ds_read2st64_b32 v[136:137], v64 offset0:48 offset1:49
	ds_read2st64_b32 v[138:139], v64 offset0:50 offset1:51
	s_waitcnt vmcnt(0)
	ds_read2st64_b32 v[140:141], v64 offset0:52 offset1:53
	ds_read2st64_b32 v[142:143], v64 offset0:54 offset1:55
	s_waitcnt lgkmcnt(14)
	v_pk_mul_f32 v[78:79], s[12:13], v[78:79]
	v_pk_mul_f32 v[80:81], s[12:13], v[80:81]
	v_pk_fma_f32 v[86:87], v[0:1], v[70:71], v[78:79] op_sel_hi:[1,0,1] neg_lo:[0,0,1] neg_hi:[0,0,1]
	v_pk_mul_f32 v[0:1], s[12:13], v[84:85]
	v_pk_fma_f32 v[2:3], v[2:3], v[70:71], v[80:81] op_sel_hi:[1,0,1] neg_lo:[0,0,1] neg_hi:[0,0,1]
	v_pk_fma_f32 v[78:79], v[6:7], v[70:71], v[0:1] op_sel_hi:[1,0,1] neg_lo:[0,0,1] neg_hi:[0,0,1]
	v_pk_mul_f32 v[0:1], s[12:13], v[82:83]
	s_waitcnt lgkmcnt(5)
	v_pk_mul_f32 v[64:65], s[12:13], v[66:67]
	v_pk_fma_f32 v[88:89], v[4:5], v[70:71], v[0:1] op_sel_hi:[1,0,1] neg_lo:[0,0,1] neg_hi:[0,0,1]
	v_pk_mul_f32 v[0:1], s[12:13], v[92:93]
	v_pk_fma_f32 v[64:65], v[60:61], v[70:71], v[64:65] op_sel_hi:[1,0,1] neg_lo:[0,0,1] neg_hi:[0,0,1]
	v_pk_fma_f32 v[80:81], v[10:11], v[70:71], v[0:1] op_sel_hi:[1,0,1] neg_lo:[0,0,1] neg_hi:[0,0,1]
	v_pk_mul_f32 v[0:1], s[12:13], v[90:91]
	s_waitcnt lgkmcnt(4)
	v_pk_mul_f32 v[60:61], s[12:13], v[68:69]
	v_pk_fma_f32 v[94:95], v[8:9], v[70:71], v[0:1] op_sel_hi:[1,0,1] neg_lo:[0,0,1] neg_hi:[0,0,1]
	v_pk_mul_f32 v[0:1], s[12:13], v[98:99]
	s_mov_b32 s1, -1
	v_pk_fma_f32 v[82:83], v[14:15], v[70:71], v[0:1] op_sel_hi:[1,0,1] neg_lo:[0,0,1] neg_hi:[0,0,1]
	v_pk_mul_f32 v[0:1], s[12:13], v[96:97]
	v_pk_fma_f32 v[66:67], v[62:63], v[70:71], v[60:61] op_sel_hi:[1,0,1] neg_lo:[0,0,1] neg_hi:[0,0,1]
	v_pk_fma_f32 v[96:97], v[12:13], v[70:71], v[0:1] op_sel_hi:[1,0,1] neg_lo:[0,0,1] neg_hi:[0,0,1]
	v_pk_mul_f32 v[0:1], s[12:13], v[102:103]
	s_waitcnt lgkmcnt(1)
	v_pk_mul_f32 v[4:5], s[12:13], v[140:141]
	v_pk_fma_f32 v[84:85], v[34:35], v[70:71], v[0:1] op_sel_hi:[1,0,1] neg_lo:[0,0,1] neg_hi:[0,0,1]
	v_pk_mul_f32 v[0:1], s[12:13], v[100:101]
	v_mbcnt_lo_u32_b32 v60, s1, 0
	v_pk_fma_f32 v[90:91], v[32:33], v[70:71], v[0:1] op_sel_hi:[1,0,1] neg_lo:[0,0,1] neg_hi:[0,0,1]
	v_pk_mul_f32 v[0:1], s[12:13], v[106:107]
	v_mbcnt_hi_u32_b32 v60, s1, v60
	v_pk_fma_f32 v[14:15], v[38:39], v[70:71], v[0:1] op_sel_hi:[1,0,1] neg_lo:[0,0,1] neg_hi:[0,0,1]
	v_pk_mul_f32 v[0:1], s[12:13], v[104:105]
	v_lshlrev_b32_e32 v60, 2, v60
	v_pk_fma_f32 v[92:93], v[36:37], v[70:71], v[0:1] op_sel_hi:[1,0,1] neg_lo:[0,0,1] neg_hi:[0,0,1]
	v_pk_mul_f32 v[0:1], s[12:13], v[110:111]
	v_xor_b32_e32 v208, 0x80, v60
	v_pk_fma_f32 v[32:33], v[42:43], v[70:71], v[0:1] op_sel_hi:[1,0,1] neg_lo:[0,0,1] neg_hi:[0,0,1]
	v_pk_mul_f32 v[0:1], s[12:13], v[108:109]
	v_ashrrev_i32_e32 v60, 3, v71
	v_pk_fma_f32 v[40:41], v[40:41], v[70:71], v[0:1] op_sel_hi:[1,0,1] neg_lo:[0,0,1] neg_hi:[0,0,1]
	v_pk_mul_f32 v[0:1], s[12:13], v[114:115]
	v_and_b32_e32 v74, -4, v60
	v_pk_fma_f32 v[34:35], v[46:47], v[70:71], v[0:1] op_sel_hi:[1,0,1] neg_lo:[0,0,1] neg_hi:[0,0,1]
	v_pk_mul_f32 v[0:1], s[12:13], v[112:113]
	v_ashrrev_i32_e32 v75, 31, v74
	v_pk_fma_f32 v[42:43], v[44:45], v[70:71], v[0:1] op_sel_hi:[1,0,1] neg_lo:[0,0,1] neg_hi:[0,0,1]
	v_pk_mul_f32 v[0:1], s[12:13], v[118:119]
	v_lshl_add_u64 v[68:69], v[74:75], 2, s[14:15]
	v_pk_fma_f32 v[18:19], v[18:19], v[70:71], v[0:1] op_sel_hi:[1,0,1] neg_lo:[0,0,1] neg_hi:[0,0,1]
	v_pk_mul_f32 v[0:1], s[12:13], v[116:117]
	v_pk_mul_f32 v[198:199], v[86:87], v[86:87]
	v_pk_fma_f32 v[36:37], v[16:17], v[70:71], v[0:1] op_sel_hi:[1,0,1] neg_lo:[0,0,1] neg_hi:[0,0,1]
	v_pk_mul_f32 v[0:1], s[12:13], v[122:123]
	global_load_dwordx4 v[232:235], v[68:69], off
	global_load_dwordx4 v[236:239], v[68:69], off offset:32
	global_load_dwordx4 v[240:243], v[68:69], off offset:64
	global_load_dwordx4 v[244:247], v[68:69], off offset:96
	global_load_dwordx4 v[248:251], v[68:69], off offset:128
	v_pk_fma_f32 v[6:7], v[22:23], v[70:71], v[0:1] op_sel_hi:[1,0,1] neg_lo:[0,0,1] neg_hi:[0,0,1]
; DI unsigned pk2(float lo, float hi) { f32x2_t v = {lo, hi}; bf16x2_t b = __builtin_convertvector(v, bf16x2_t); return __builtin_bit_cast(unsigned, b); }
; DI float shflx(float v, int mask) { return __uint_as_float((unsigned)__builtin_amdgcn_ds_bpermute((lane_id_opaque() ^ mask) << 2, (int)__float_as_uint(v))); }
; template <bool DIFF> DI void attn_unit(LAS unsigned char* L, const bf16* Qh, int qpitch, const bf16* Kh, const bf16* Vh, int kvpitch, bf16* Oh, int opitch, ...
;     ...
;             for (int d0 = 0; d0 < 4; ++d0)
; #pragma unroll
;                 for (int i = 0; i < 16; ++i) { const float o = y[d0][i] * inv - lam * exch[((qs * 4 + d0) * 16 + i) * 64 + le_]; y[d0][i] = o; ss += o * o; }
;             ss += shflx(ss, 32);
;             const float rr = rsqrtf(ss * (1.f / 128.f) + EPS) * postscale;
; #pragma unroll
;             for (int d0 = 0; d0 < 4; ++d0)
; #pragma unroll
;                 for (int g = 0; g < 4; ++g) { const int dv0 = 32 * d0 + 8 * g + 4 * h_e; const f32x4 sg = *(const f32x4*)(subg + dv0);
;                     u32x2 w; w.x = pk2(y[d0][4 * g] * rr * sg.x, y[d0][4 * g + 1] * rr * sg.y); w.y = pk2(y[d0][4 * g + 2] * rr * sg.z, y[d0][4 * g + 3] * rr * sg.w);
	v_pk_mul_f32 v[0:1], s[12:13], v[120:121]
	v_pk_mul_f32 v[22:23], s[12:13], v[132:133]
	v_pk_fma_f32 v[38:39], v[20:21], v[70:71], v[0:1] op_sel_hi:[1,0,1] neg_lo:[0,0,1] neg_hi:[0,0,1]
	v_pk_mul_f32 v[0:1], s[12:13], v[126:127]
	v_pk_fma_f32 v[20:21], v[52:53], v[70:71], v[4:5] op_sel_hi:[1,0,1] neg_lo:[0,0,1] neg_hi:[0,0,1]
	v_pk_fma_f32 v[8:9], v[26:27], v[70:71], v[0:1] op_sel_hi:[1,0,1] neg_lo:[0,0,1] neg_hi:[0,0,1]
	v_pk_mul_f32 v[0:1], s[12:13], v[124:125]
	v_pk_mul_f32 v[4:5], s[12:13], v[134:135]
	v_pk_fma_f32 v[24:25], v[24:25], v[70:71], v[0:1] op_sel_hi:[1,0,1] neg_lo:[0,0,1] neg_hi:[0,0,1]
	v_pk_mul_f32 v[0:1], s[12:13], v[130:131]
	v_pk_mul_f32 v[196:197], v[2:3], v[2:3]
	v_pk_fma_f32 v[10:11], v[30:31], v[70:71], v[0:1] op_sel_hi:[1,0,1] neg_lo:[0,0,1] neg_hi:[0,0,1]
	v_pk_mul_f32 v[0:1], s[12:13], v[128:129]
	v_pk_fma_f32 v[4:5], v[58:59], v[70:71], v[4:5] op_sel_hi:[1,0,1] neg_lo:[0,0,1] neg_hi:[0,0,1]
	v_pk_fma_f32 v[26:27], v[28:29], v[70:71], v[0:1] op_sel_hi:[1,0,1] neg_lo:[0,0,1] neg_hi:[0,0,1]
	v_pk_mul_f32 v[0:1], s[12:13], v[138:139]
	v_pk_fma_f32 v[22:23], v[56:57], v[70:71], v[22:23] op_sel_hi:[1,0,1] neg_lo:[0,0,1] neg_hi:[0,0,1]
	v_pk_fma_f32 v[12:13], v[50:51], v[70:71], v[0:1] op_sel_hi:[1,0,1] neg_lo:[0,0,1] neg_hi:[0,0,1]
	v_pk_mul_f32 v[0:1], s[12:13], v[136:137]
	v_pk_mul_f32 v[222:223], v[88:89], v[88:89]
	v_pk_fma_f32 v[16:17], v[48:49], v[70:71], v[0:1] op_sel_hi:[1,0,1] neg_lo:[0,0,1] neg_hi:[0,0,1]
	s_waitcnt lgkmcnt(0)
	v_pk_mul_f32 v[0:1], s[12:13], v[142:143]
	v_pk_mul_f32 v[220:221], v[78:79], v[78:79]
	v_pk_fma_f32 v[0:1], v[54:55], v[70:71], v[0:1] op_sel_hi:[1,0,1] neg_lo:[0,0,1] neg_hi:[0,0,1]
	v_add_f32_e32 v70, v198, v199
	v_add_f32_e32 v70, v70, v196
	v_add_f32_e32 v70, v70, v197
	v_add_f32_e32 v70, v70, v222
	v_add_f32_e32 v70, v70, v223
	v_add_f32_e32 v70, v70, v220
	v_pk_mul_f32 v[226:227], v[94:95], v[94:95]
	v_add_f32_e32 v70, v70, v221
	v_add_f32_e32 v70, v70, v226
	v_pk_mul_f32 v[224:225], v[80:81], v[80:81]
	v_add_f32_e32 v70, v70, v227
	v_add_f32_e32 v70, v70, v224
	v_pk_mul_f32 v[228:229], v[96:97], v[96:97]
	v_add_f32_e32 v70, v70, v225
	v_add_f32_e32 v70, v70, v228
	v_pk_mul_f32 v[98:99], v[82:83], v[82:83]
	v_add_f32_e32 v70, v70, v229
	v_add_f32_e32 v70, v70, v98
	v_pk_mul_f32 v[100:101], v[90:91], v[90:91]
	v_add_f32_e32 v70, v70, v99
	v_add_f32_e32 v70, v70, v100
	v_pk_mul_f32 v[102:103], v[84:85], v[84:85]
	v_add_f32_e32 v70, v70, v101
	v_add_f32_e32 v70, v70, v102
	v_pk_mul_f32 v[104:105], v[92:93], v[92:93]
	v_add_f32_e32 v70, v70, v103
	v_add_f32_e32 v70, v70, v104
	v_pk_mul_f32 v[106:107], v[14:15], v[14:15]
	v_add_f32_e32 v70, v70, v105
	v_add_f32_e32 v70, v70, v106
	v_pk_mul_f32 v[108:109], v[40:41], v[40:41]
	v_add_f32_e32 v70, v70, v107
	v_add_f32_e32 v70, v70, v108
	v_pk_mul_f32 v[110:111], v[32:33], v[32:33]
	v_add_f32_e32 v70, v70, v109
	v_add_f32_e32 v70, v70, v110
	v_pk_mul_f32 v[44:45], v[42:43], v[42:43]
	v_add_f32_e32 v70, v70, v111
	v_add_f32_e32 v44, v70, v44
	v_pk_mul_f32 v[46:47], v[34:35], v[34:35]
	v_add_f32_e32 v44, v44, v45
	v_add_f32_e32 v44, v44, v46
	v_pk_mul_f32 v[114:115], v[36:37], v[36:37]
	v_add_f32_e32 v44, v44, v47
	v_add_f32_e32 v44, v44, v114
	v_pk_mul_f32 v[112:113], v[18:19], v[18:19]
	v_add_f32_e32 v44, v44, v115
	v_add_f32_e32 v44, v44, v112
	v_pk_mul_f32 v[118:119], v[38:39], v[38:39]
	v_add_f32_e32 v44, v44, v113
	v_add_f32_e32 v44, v44, v118
	v_pk_mul_f32 v[116:117], v[6:7], v[6:7]
	v_add_f32_e32 v44, v44, v119
	v_add_f32_e32 v44, v44, v116
	v_pk_mul_f32 v[122:123], v[24:25], v[24:25]
	v_add_f32_e32 v44, v44, v117
	v_add_f32_e32 v44, v44, v122
	v_pk_mul_f32 v[120:121], v[8:9], v[8:9]
	v_add_f32_e32 v44, v44, v123
	v_add_f32_e32 v44, v44, v120
	v_pk_mul_f32 v[28:29], v[26:27], v[26:27]
	v_add_f32_e32 v44, v44, v121
	v_add_f32_e32 v28, v44, v28
	v_pk_mul_f32 v[30:31], v[10:11], v[10:11]
	v_add_f32_e32 v28, v28, v29
	v_add_f32_e32 v28, v28, v30
	v_pk_mul_f32 v[48:49], v[16:17], v[16:17]
	v_add_f32_e32 v28, v28, v31
	v_add_f32_e32 v28, v28, v48
	v_pk_mul_f32 v[50:51], v[12:13], v[12:13]
	v_add_f32_e32 v28, v28, v49
	v_add_f32_e32 v28, v28, v50
	v_pk_mul_f32 v[52:53], v[20:21], v[20:21]
	v_add_f32_e32 v28, v28, v51
	v_add_f32_e32 v28, v28, v52
	v_pk_mul_f32 v[54:55], v[0:1], v[0:1]
	v_add_f32_e32 v28, v28, v53
	v_add_f32_e32 v28, v28, v54
	v_pk_mul_f32 v[56:57], v[22:23], v[22:23]
	v_add_f32_e32 v28, v28, v55
	v_add_f32_e32 v28, v28, v56
	v_pk_mul_f32 v[58:59], v[4:5], v[4:5]
	v_add_f32_e32 v28, v28, v57
	v_add_f32_e32 v28, v28, v58
	v_pk_mul_f32 v[72:73], v[64:65], v[64:65]
	v_add_f32_e32 v28, v28, v59
	v_add_f32_e32 v28, v28, v72
	v_pk_mul_f32 v[76:77], v[66:67], v[66:67]
	v_add_f32_e32 v28, v28, v73
	v_add_f32_e32 v28, v28, v76
	v_add_f32_e32 v44, v28, v77
	ds_bpermute_b32 v45, v208, v44
	s_lshl_b32 s36, s80, 1
	v_and_or_b32 v30, v71, 31, s74
	v_mov_b32_e32 v31, s75
	v_lshl_add_u64 v[28:29], v[144:145], 0, s[36:37]
	s_waitcnt lgkmcnt(0)
	v_add_f32_e32 v44, v44, v45
	v_fmamk_f32 v44, v44, 0x3c000000, v203
	v_mul_f32_e32 v45, 0x4b800000, v44
	v_cmp_gt_f32_e32 vcc, s2, v44
	v_lshlrev_b64 v[30:31], 12, v[30:31]
	v_lshl_add_u64 v[28:29], v[28:29], 0, v[30:31]
	v_cndmask_b32_e32 v44, v44, v45, vcc
	v_rsq_f32_e32 v46, v44
	v_lshl_add_u64 v[44:45], v[74:75], 1, v[28:29]
	v_mul_f32_e32 v28, 0x45800000, v46
	v_cndmask_b32_e32 v28, v46, v28, vcc
	v_mul_f32_e32 v46, v209, v28
	v_pk_mul_f32 v[28:29], v[86:87], v[46:47] op_sel_hi:[1,0]
	v_pk_mul_f32 v[2:3], v[2:3], v[46:47] op_sel_hi:[1,0]
	s_waitcnt vmcnt(4)
; DI unsigned pk2(float lo, float hi) { f32x2_t v = {lo, hi}; bf16x2_t b = __builtin_convertvector(v, bf16x2_t); return __builtin_bit_cast(unsigned, b); }
; template <bool DIFF> DI void attn_unit(LAS unsigned char* L, const bf16* Qh, int qpitch, const bf16* Kh, const bf16* Vh, int kvpitch, bf16* Oh, int opitch, ...
;     ...
; #pragma unroll
;             for (int d0 = 0; d0 < 4; ++d0)
; #pragma unroll
;                 for (int g = 0; g < 4; ++g) { const int dv0 = 32 * d0 + 8 * g + 4 * h_e; const f32x4 sg = *(const f32x4*)(subg + dv0);
;                     u32x2 w; w.x = pk2(y[d0][4 * g] * rr * sg.x, y[d0][4 * g + 1] * rr * sg.y); w.y = pk2(y[d0][4 * g + 2] * rr * sg.z, y[d0][4 * g + 3] * rr * sg.w);
;                     *(u32x2*)(orow + dv0) = w; }
	v_pk_mul_f32 v[28:29], v[232:233], v[28:29]
	v_pk_mul_f32 v[2:3], v[234:235], v[2:3]
	v_cvt_pk_bf16_f32 v28, v28, v29
	v_cvt_pk_bf16_f32 v29, v2, v3
	global_store_dwordx2 v[44:45], v[28:29], off
	global_load_dwordx4 v[232:235], v[68:69], off offset:160
	v_pk_mul_f32 v[2:3], v[88:89], v[46:47] op_sel_hi:[1,0]
	v_pk_mul_f32 v[48:49], v[80:81], v[46:47] op_sel_hi:[1,0]
	v_pk_mul_f32 v[14:15], v[14:15], v[46:47] op_sel_hi:[1,0]
	v_pk_mul_f32 v[6:7], v[6:7], v[46:47] op_sel_hi:[1,0]
	v_pk_mul_f32 v[10:11], v[10:11], v[46:47] op_sel_hi:[1,0]
	v_pk_mul_f32 v[0:1], v[0:1], v[46:47] op_sel_hi:[1,0]
	v_pk_mul_f32 v[4:5], v[4:5], v[46:47] op_sel_hi:[1,0]
	s_waitcnt vmcnt(5)
	v_pk_mul_f32 v[2:3], v[236:237], v[2:3]
	v_pk_mul_f32 v[28:29], v[78:79], v[46:47] op_sel_hi:[1,0]
	v_cvt_pk_bf16_f32 v2, v2, v3
	v_pk_mul_f32 v[28:29], v[238:239], v[28:29]
	s_nop 0
	v_cvt_pk_bf16_f32 v3, v28, v29
	global_store_dwordx2 v[44:45], v[2:3], off offset:16
	global_load_dwordx4 v[236:239], v[68:69], off offset:192
	v_pk_mul_f32 v[2:3], v[94:95], v[46:47] op_sel_hi:[1,0]
	s_waitcnt vmcnt(6)
	v_pk_mul_f32 v[2:3], v[240:241], v[2:3]
	v_pk_mul_f32 v[28:29], v[242:243], v[48:49]
	v_cvt_pk_bf16_f32 v2, v2, v3
	v_cvt_pk_bf16_f32 v3, v28, v29
	global_store_dwordx2 v[44:45], v[2:3], off offset:32
	global_load_dwordx4 v[240:243], v[68:69], off offset:224
	v_pk_mul_f32 v[2:3], v[96:97], v[46:47] op_sel_hi:[1,0]
	v_pk_mul_f32 v[48:49], v[82:83], v[46:47] op_sel_hi:[1,0]
	s_waitcnt vmcnt(7)
	v_pk_mul_f32 v[2:3], v[244:245], v[2:3]
	v_pk_mul_f32 v[28:29], v[246:247], v[48:49]
	v_cvt_pk_bf16_f32 v2, v2, v3
	v_cvt_pk_bf16_f32 v3, v28, v29
	global_store_dwordx2 v[44:45], v[2:3], off offset:48
	global_load_dwordx4 v[244:247], v[68:69], off offset:256
	v_pk_mul_f32 v[2:3], v[90:91], v[46:47] op_sel_hi:[1,0]
	v_pk_mul_f32 v[48:49], v[84:85], v[46:47] op_sel_hi:[1,0]
	s_waitcnt vmcnt(8)
	v_pk_mul_f32 v[2:3], v[248:249], v[2:3]
	v_pk_mul_f32 v[28:29], v[250:251], v[48:49]
	v_cvt_pk_bf16_f32 v2, v2, v3
	v_cvt_pk_bf16_f32 v3, v28, v29
	global_store_dwordx2 v[44:45], v[2:3], off offset:64
	global_load_dwordx4 v[248:251], v[68:69], off offset:288
	v_pk_mul_f32 v[2:3], v[92:93], v[46:47] op_sel_hi:[1,0]
	s_waitcnt vmcnt(8)
	v_pk_mul_f32 v[14:15], v[14:15], v[234:235]
	v_pk_mul_f32 v[2:3], v[2:3], v[232:233]
	s_nop 0
	v_cvt_pk_bf16_f32 v2, v2, v3
	v_cvt_pk_bf16_f32 v3, v14, v15
	global_store_dwordx2 v[44:45], v[2:3], off offset:80
	global_load_dwordx4 v[232:235], v[68:69], off offset:320
	v_pk_mul_f32 v[2:3], v[40:41], v[46:47] op_sel_hi:[1,0]
	v_pk_mul_f32 v[14:15], v[32:33], v[46:47] op_sel_hi:[1,0]
	s_waitcnt vmcnt(8)
	v_pk_mul_f32 v[2:3], v[2:3], v[236:237]
	v_pk_mul_f32 v[14:15], v[14:15], v[238:239]
	v_cvt_pk_bf16_f32 v2, v2, v3
	v_cvt_pk_bf16_f32 v3, v14, v15
	global_store_dwordx2 v[44:45], v[2:3], off offset:96
	global_load_dwordx4 v[236:239], v[68:69], off offset:352
	v_pk_mul_f32 v[2:3], v[42:43], v[46:47] op_sel_hi:[1,0]
	v_pk_mul_f32 v[14:15], v[34:35], v[46:47] op_sel_hi:[1,0]
	s_waitcnt vmcnt(8)
	v_pk_mul_f32 v[2:3], v[2:3], v[240:241]
	v_pk_mul_f32 v[14:15], v[14:15], v[242:243]
	v_cvt_pk_bf16_f32 v2, v2, v3
	v_cvt_pk_bf16_f32 v3, v14, v15
	global_store_dwordx2 v[44:45], v[2:3], off offset:112
	global_load_dwordx4 v[240:243], v[68:69], off offset:384
	v_pk_mul_f32 v[2:3], v[36:37], v[46:47] op_sel_hi:[1,0]
	v_pk_mul_f32 v[14:15], v[18:19], v[46:47] op_sel_hi:[1,0]
	s_waitcnt vmcnt(8)
	v_pk_mul_f32 v[2:3], v[2:3], v[244:245]
	v_pk_mul_f32 v[14:15], v[14:15], v[246:247]
	v_cvt_pk_bf16_f32 v2, v2, v3
	v_cvt_pk_bf16_f32 v3, v14, v15
	global_store_dwordx2 v[44:45], v[2:3], off offset:128
	global_load_dwordx4 v[244:247], v[68:69], off offset:416
	v_pk_mul_f32 v[2:3], v[38:39], v[46:47] op_sel_hi:[1,0]
	s_waitcnt vmcnt(8)
	v_pk_mul_f32 v[6:7], v[6:7], v[250:251]
	v_pk_mul_f32 v[2:3], v[2:3], v[248:249]
	s_nop 0
	v_cvt_pk_bf16_f32 v2, v2, v3
	v_cvt_pk_bf16_f32 v3, v6, v7
	global_store_dwordx2 v[44:45], v[2:3], off offset:144
	global_load_dwordx4 v[248:251], v[68:69], off offset:448
	v_pk_mul_f32 v[2:3], v[24:25], v[46:47] op_sel_hi:[1,0]
	v_pk_mul_f32 v[6:7], v[8:9], v[46:47] op_sel_hi:[1,0]
	s_waitcnt vmcnt(8)
	v_pk_mul_f32 v[2:3], v[2:3], v[232:233]
	v_pk_mul_f32 v[6:7], v[6:7], v[234:235]
	v_cvt_pk_bf16_f32 v2, v2, v3
	v_cvt_pk_bf16_f32 v3, v6, v7
	global_store_dwordx2 v[44:45], v[2:3], off offset:160
	global_load_dwordx4 v[232:235], v[68:69], off offset:480
	v_pk_mul_f32 v[2:3], v[26:27], v[46:47] op_sel_hi:[1,0]
	s_waitcnt vmcnt(8)
	v_pk_mul_f32 v[2:3], v[2:3], v[236:237]
	v_pk_mul_f32 v[6:7], v[10:11], v[238:239]
	v_cvt_pk_bf16_f32 v2, v2, v3
	v_cvt_pk_bf16_f32 v3, v6, v7
	global_store_dwordx2 v[44:45], v[2:3], off offset:176
	v_pk_mul_f32 v[2:3], v[16:17], v[46:47] op_sel_hi:[1,0]
	v_pk_mul_f32 v[10:11], v[12:13], v[46:47] op_sel_hi:[1,0]
	s_waitcnt vmcnt(7)
	v_pk_mul_f32 v[2:3], v[2:3], v[240:241]
	v_pk_mul_f32 v[6:7], v[10:11], v[242:243]
	v_cvt_pk_bf16_f32 v2, v2, v3
	v_cvt_pk_bf16_f32 v3, v6, v7
	global_store_dwordx2 v[44:45], v[2:3], off offset:192
	v_pk_mul_f32 v[2:3], v[20:21], v[46:47] op_sel_hi:[1,0]
	s_waitcnt vmcnt(6)
	v_pk_mul_f32 v[0:1], v[0:1], v[246:247]
	v_pk_mul_f32 v[2:3], v[2:3], v[244:245]
	v_pk_mul_f32 v[6:7], v[22:23], v[46:47] op_sel_hi:[1,0]
	v_cvt_pk_bf16_f32 v2, v2, v3
	v_cvt_pk_bf16_f32 v3, v0, v1
	global_store_dwordx2 v[44:45], v[2:3], off offset:208
	s_waitcnt vmcnt(5)
	v_pk_mul_f32 v[0:1], v[6:7], v[248:249]
	v_pk_mul_f32 v[2:3], v[4:5], v[250:251]
	v_cvt_pk_bf16_f32 v0, v0, v1
	v_cvt_pk_bf16_f32 v1, v2, v3
	global_store_dwordx2 v[44:45], v[0:1], off offset:224
	v_pk_mul_f32 v[4:5], v[64:65], v[46:47] op_sel_hi:[1,0]
	v_pk_mul_f32 v[6:7], v[66:67], v[46:47] op_sel_hi:[1,0]
	s_waitcnt vmcnt(4)
	v_pk_mul_f32 v[0:1], v[4:5], v[232:233]
	v_pk_mul_f32 v[2:3], v[6:7], v[234:235]
	v_cvt_pk_bf16_f32 v0, v0, v1
	v_cvt_pk_bf16_f32 v1, v2, v3
	global_store_dwordx2 v[44:45], v[0:1], off offset:240
	s_branch .LBB0_166
